# conv loop rewrite + final-norm loop (gain hoisted, next row prefetched) + HGRN chunk-state scan double-buffered
# speedup vs baseline: 1.0082x; 1.0056x over previous
; __device__ __forceinline__ float bflo(unsigned w) { return __uint_as_float(w << 16); }
; __device__ __forceinline__ float bfhi(unsigned w) { return __uint_as_float(w & 0xffff0000u); }
; __global__ void __launch_bounds__(512, 2) mega(Params p, int ph_lo, int ph_hi) {
;     ...
;         if (rep == 0) for (int gid = bid * 512 + wave * 64 + lane2; gid < 131072; gid += NGT) {
;             const int bh = gid >> 13, e = gid & 8191, v = e >> 6, k2 = (e & 63) * 2;
;             f32x2 s = {0.f, 0.f};
;             unsigned* base = (unsigned*)(SSTB + ((size_t)bh * 128 * 128 + v) * 128 + k2);
;             const float* dbase = DK + (size_t)bh * 128 * 128 + k2;
; #pragma unroll 1
;             for (int c0 = 0; c0 < 128; c0 += 8) {
;                 unsigned tw[8]; f32x2 dd[8];
; #pragma unroll
;                 for (int u = 0; u < 8; ++u) { tw[u] = base[(size_t)(c0 + u) * 8192]; dd[u] = *(const f32x2*)(dbase + (size_t)(c0 + u) * 128); }
; #pragma unroll
;                 for (int u = 0; u < 8; ++u) { base[(size_t)(c0 + u) * 8192] = pk2(s.x, s.y); s = dd[u] * s + (f32x2){bflo(tw[u]), bfhi(tw[u])}; }
;             }
.LBB0_398:
	v_lshlrev_b32_e32 v0, 2, v6
	v_ashrrev_i32_e32 v2, 13, v6
	v_and_b32_e32 v4, 0x7f00, v0
	v_lshlrev_b32_e32 v0, 1, v7
	v_ashrrev_i32_e32 v3, 31, v2
	v_and_b32_e32 v5, 0xfc, v0
	v_lshlrev_b32_e32 v8, 2, v7
	v_lshlrev_b64 v[0:1], 22, v[2:3]
	v_lshlrev_b64 v[2:3], 16, v[2:3]
	v_or3_b32 v0, v0, v4, v5
	v_and_or_b32 v2, v8, s14, v2
	v_mov_b32_e32 v4, 0
	v_lshl_add_u64 v[0:1], s[4:5], 0, v[0:1]
	v_lshl_add_u64 v[2:3], s[6:7], 0, v[2:3]
	s_mov_b32 s16, -8
	v_mov_b32_e32 v5, v4
	v_mov_b32_e32 v48, v0
	v_mov_b32_e32 v49, v1
	v_add_co_u32_e32 v8, vcc, 0xfffc8000, v48
	s_nop 1
	v_addc_co_u32_e32 v9, vcc, -1, v49, vcc
	v_add_co_u32_e32 v12, vcc, 0xfffd0000, v48
	s_nop 1
	v_addc_co_u32_e32 v13, vcc, -1, v49, vcc
	v_add_co_u32_e32 v14, vcc, 0xfffd8000, v48
	s_nop 1
	v_addc_co_u32_e32 v15, vcc, -1, v49, vcc
	v_add_co_u32_e32 v16, vcc, 0xfffe0000, v48
	s_nop 1
	v_addc_co_u32_e32 v17, vcc, -1, v49, vcc
	v_add_co_u32_e32 v24, vcc, 0xfffe8000, v48
	s_nop 1
	v_addc_co_u32_e32 v25, vcc, -1, v49, vcc
	v_add_co_u32_e32 v26, vcc, 0xffff0000, v48
	s_nop 1
	v_addc_co_u32_e32 v27, vcc, -1, v49, vcc
	v_add_co_u32_e32 v32, vcc, 0xffff8000, v48
	s_nop 1
	v_addc_co_u32_e32 v33, vcc, -1, v49, vcc
	v_mov_b32_e32 v0, v48
	v_mov_b32_e32 v1, v49
	global_load_dword v39, v[8:9], off
	global_load_dword v40, v[12:13], off
	global_load_dword v41, v[14:15], off
	global_load_dword v42, v[16:17], off
	global_load_dword v43, v[24:25], off
	global_load_dword v44, v[26:27], off
	global_load_dword v45, v[32:33], off
	global_load_dword v38, v[0:1], off
	global_load_dwordx2 v[10:11], v[2:3], off
	global_load_dwordx2 v[18:19], v[2:3], off offset:512
	global_load_dwordx2 v[20:21], v[2:3], off offset:1024
	global_load_dwordx2 v[22:23], v[2:3], off offset:1536
	global_load_dwordx2 v[28:29], v[2:3], off offset:2048
	global_load_dwordx2 v[30:31], v[2:3], off offset:2560
	global_load_dwordx2 v[34:35], v[2:3], off offset:3072
	global_load_dwordx2 v[36:37], v[2:3], off offset:3584
	v_lshl_add_u64 v[2:3], v[2:3], 0, s[12:13]
	v_lshl_add_u64 v[48:49], v[48:49], 0, s[10:11]
.LBB0_399:
	s_add_i32 s16, s16, 16
	v_add_co_u32_e32 v68, vcc, 0xfffc8000, v48
	s_nop 1
	v_addc_co_u32_e32 v69, vcc, -1, v49, vcc
	v_add_co_u32_e32 v72, vcc, 0xfffd0000, v48
	s_nop 1
	v_addc_co_u32_e32 v73, vcc, -1, v49, vcc
	v_add_co_u32_e32 v74, vcc, 0xfffd8000, v48
	s_nop 1
	v_addc_co_u32_e32 v75, vcc, -1, v49, vcc
	v_add_co_u32_e32 v76, vcc, 0xfffe0000, v48
	s_nop 1
	v_addc_co_u32_e32 v77, vcc, -1, v49, vcc
	v_add_co_u32_e32 v84, vcc, 0xfffe8000, v48
	s_nop 1
	v_addc_co_u32_e32 v85, vcc, -1, v49, vcc
	v_add_co_u32_e32 v86, vcc, 0xffff0000, v48
	s_nop 1
	v_addc_co_u32_e32 v87, vcc, -1, v49, vcc
	v_add_co_u32_e32 v92, vcc, 0xffff8000, v48
	s_nop 1
	v_addc_co_u32_e32 v93, vcc, -1, v49, vcc
	v_mov_b32_e32 v60, v48
	v_mov_b32_e32 v61, v49
	global_load_dword v99, v[68:69], off
	global_load_dword v100, v[72:73], off
	global_load_dword v101, v[74:75], off
	global_load_dword v102, v[76:77], off
	global_load_dword v103, v[84:85], off
	global_load_dword v104, v[86:87], off
	global_load_dword v105, v[92:93], off
	global_load_dword v98, v[60:61], off
	global_load_dwordx2 v[70:71], v[2:3], off
	global_load_dwordx2 v[78:79], v[2:3], off offset:512
	global_load_dwordx2 v[80:81], v[2:3], off offset:1024
	global_load_dwordx2 v[82:83], v[2:3], off offset:1536
	global_load_dwordx2 v[88:89], v[2:3], off offset:2048
	global_load_dwordx2 v[90:91], v[2:3], off offset:2560
	global_load_dwordx2 v[94:95], v[2:3], off offset:3072
	global_load_dwordx2 v[96:97], v[2:3], off offset:3584
	v_lshl_add_u64 v[2:3], v[2:3], 0, s[12:13]
	v_lshl_add_u64 v[48:49], v[48:49], 0, s[10:11]
	s_waitcnt vmcnt(16)
	v_cvt_pk_bf16_f32 v46, v4, v5
	v_lshlrev_b32_e32 v50, 16, v39
	v_and_b32_e32 v51, 0xffff0000, v39
	global_store_dword v[8:9], v46, off
	v_pk_fma_f32 v[4:5], v[4:5], v[10:11], v[50:51]
	v_cvt_pk_bf16_f32 v46, v4, v5
	v_lshlrev_b32_e32 v50, 16, v40
	v_and_b32_e32 v51, 0xffff0000, v40
	global_store_dword v[12:13], v46, off
	v_pk_fma_f32 v[4:5], v[4:5], v[18:19], v[50:51]
	v_cvt_pk_bf16_f32 v46, v4, v5
	v_lshlrev_b32_e32 v50, 16, v41
	v_and_b32_e32 v51, 0xffff0000, v41
	global_store_dword v[14:15], v46, off
	v_pk_fma_f32 v[4:5], v[4:5], v[20:21], v[50:51]
	v_cvt_pk_bf16_f32 v46, v4, v5
	v_lshlrev_b32_e32 v50, 16, v42
	v_and_b32_e32 v51, 0xffff0000, v42
	global_store_dword v[16:17], v46, off
	v_pk_fma_f32 v[4:5], v[4:5], v[22:23], v[50:51]
	v_cvt_pk_bf16_f32 v46, v4, v5
	v_lshlrev_b32_e32 v50, 16, v43
	v_and_b32_e32 v51, 0xffff0000, v43
	global_store_dword v[24:25], v46, off
	v_pk_fma_f32 v[4:5], v[4:5], v[28:29], v[50:51]
	v_cvt_pk_bf16_f32 v46, v4, v5
	v_lshlrev_b32_e32 v50, 16, v44
	v_and_b32_e32 v51, 0xffff0000, v44
	global_store_dword v[26:27], v46, off
	v_pk_fma_f32 v[4:5], v[4:5], v[30:31], v[50:51]
	v_cvt_pk_bf16_f32 v46, v4, v5
	v_lshlrev_b32_e32 v50, 16, v45
	v_and_b32_e32 v51, 0xffff0000, v45
	global_store_dword v[32:33], v46, off
	v_pk_fma_f32 v[4:5], v[4:5], v[34:35], v[50:51]
	v_cvt_pk_bf16_f32 v46, v4, v5
	v_lshlrev_b32_e32 v50, 16, v38
	v_and_b32_e32 v51, 0xffff0000, v38
	global_store_dword v[0:1], v46, off
	v_pk_fma_f32 v[4:5], v[4:5], v[36:37], v[50:51]
	s_cmpk_gt_u32 s16, 0x6f
	s_cbranch_scc1 .Lh2_lastB
	v_add_co_u32_e32 v8, vcc, 0xfffc8000, v48
	s_nop 1
	v_addc_co_u32_e32 v9, vcc, -1, v49, vcc
	v_add_co_u32_e32 v12, vcc, 0xfffd0000, v48
	s_nop 1
	v_addc_co_u32_e32 v13, vcc, -1, v49, vcc
	v_add_co_u32_e32 v14, vcc, 0xfffd8000, v48
	s_nop 1
	v_addc_co_u32_e32 v15, vcc, -1, v49, vcc
	v_add_co_u32_e32 v16, vcc, 0xfffe0000, v48
	s_nop 1
	v_addc_co_u32_e32 v17, vcc, -1, v49, vcc
	v_add_co_u32_e32 v24, vcc, 0xfffe8000, v48
	s_nop 1
	v_addc_co_u32_e32 v25, vcc, -1, v49, vcc
	v_add_co_u32_e32 v26, vcc, 0xffff0000, v48
	s_nop 1
	v_addc_co_u32_e32 v27, vcc, -1, v49, vcc
	v_add_co_u32_e32 v32, vcc, 0xffff8000, v48
	s_nop 1
	v_addc_co_u32_e32 v33, vcc, -1, v49, vcc
	v_mov_b32_e32 v0, v48
	v_mov_b32_e32 v1, v49
	global_load_dword v39, v[8:9], off
	global_load_dword v40, v[12:13], off
	global_load_dword v41, v[14:15], off
	global_load_dword v42, v[16:17], off
	global_load_dword v43, v[24:25], off
	global_load_dword v44, v[26:27], off
	global_load_dword v45, v[32:33], off
	global_load_dword v38, v[0:1], off
	global_load_dwordx2 v[10:11], v[2:3], off
	global_load_dwordx2 v[18:19], v[2:3], off offset:512
	global_load_dwordx2 v[20:21], v[2:3], off offset:1024
	global_load_dwordx2 v[22:23], v[2:3], off offset:1536
	global_load_dwordx2 v[28:29], v[2:3], off offset:2048
	global_load_dwordx2 v[30:31], v[2:3], off offset:2560
	global_load_dwordx2 v[34:35], v[2:3], off offset:3072
	global_load_dwordx2 v[36:37], v[2:3], off offset:3584
	v_lshl_add_u64 v[2:3], v[2:3], 0, s[12:13]
	v_lshl_add_u64 v[48:49], v[48:49], 0, s[10:11]
	s_waitcnt vmcnt(16)
	s_branch .Lh2_cB

; __device__ __forceinline__ float bflo(unsigned w) { return __uint_as_float(w << 16); }
; __device__ __forceinline__ float bfhi(unsigned w) { return __uint_as_float(w & 0xffff0000u); }
; __global__ void __launch_bounds__(512, 2) mega(Params p, int ph_lo, int ph_hi) {
;     ...
;             for (int c0 = 0; c0 < 128; c0 += 8) {
;                 unsigned tw[8]; f32x2 dd[8];
; #pragma unroll
;                 for (int u = 0; u < 8; ++u) { tw[u] = base[(size_t)(c0 + u) * 8192]; dd[u] = *(const f32x2*)(dbase + (size_t)(c0 + u) * 128); }
; #pragma unroll
;                 for (int u = 0; u < 8; ++u) { base[(size_t)(c0 + u) * 8192] = pk2(s.x, s.y); s = dd[u] * s + (f32x2){bflo(tw[u]), bfhi(tw[u])}; }
;             }
;         }
.Lh2_cB:
	v_cvt_pk_bf16_f32 v46, v4, v5
	v_lshlrev_b32_e32 v50, 16, v99
	v_and_b32_e32 v51, 0xffff0000, v99
	global_store_dword v[68:69], v46, off
	v_pk_fma_f32 v[4:5], v[4:5], v[70:71], v[50:51]
	v_cvt_pk_bf16_f32 v46, v4, v5
	v_lshlrev_b32_e32 v50, 16, v100
	v_and_b32_e32 v51, 0xffff0000, v100
	global_store_dword v[72:73], v46, off
	v_pk_fma_f32 v[4:5], v[4:5], v[78:79], v[50:51]
	v_cvt_pk_bf16_f32 v46, v4, v5
	v_lshlrev_b32_e32 v50, 16, v101
	v_and_b32_e32 v51, 0xffff0000, v101
	global_store_dword v[74:75], v46, off
	v_pk_fma_f32 v[4:5], v[4:5], v[80:81], v[50:51]
	v_cvt_pk_bf16_f32 v46, v4, v5
	v_lshlrev_b32_e32 v50, 16, v102
	v_and_b32_e32 v51, 0xffff0000, v102
	global_store_dword v[76:77], v46, off
	v_pk_fma_f32 v[4:5], v[4:5], v[82:83], v[50:51]
	v_cvt_pk_bf16_f32 v46, v4, v5
	v_lshlrev_b32_e32 v50, 16, v103
	v_and_b32_e32 v51, 0xffff0000, v103
	global_store_dword v[84:85], v46, off
	v_pk_fma_f32 v[4:5], v[4:5], v[88:89], v[50:51]
	v_cvt_pk_bf16_f32 v46, v4, v5
	v_lshlrev_b32_e32 v50, 16, v104
	v_and_b32_e32 v51, 0xffff0000, v104
	global_store_dword v[86:87], v46, off
	v_pk_fma_f32 v[4:5], v[4:5], v[90:91], v[50:51]
	v_cvt_pk_bf16_f32 v46, v4, v5
	v_lshlrev_b32_e32 v50, 16, v105
	v_and_b32_e32 v51, 0xffff0000, v105
	global_store_dword v[92:93], v46, off
	v_pk_fma_f32 v[4:5], v[4:5], v[94:95], v[50:51]
	v_cvt_pk_bf16_f32 v46, v4, v5
	v_lshlrev_b32_e32 v50, 16, v98
	v_and_b32_e32 v51, 0xffff0000, v98
	global_store_dword v[60:61], v46, off
	v_pk_fma_f32 v[4:5], v[4:5], v[96:97], v[50:51]
	s_cmpk_gt_u32 s16, 0x6f
	s_cbranch_scc0 .LBB0_399
	v_add_u32_e32 v6, s38, v6
	v_cmp_lt_i32_e32 vcc, s15, v6
	s_or_b64 s[8:9], vcc, s[8:9]
	v_add_u32_e32 v7, s3, v7
	s_andn2_b64 exec, exec, s[8:9]
	s_cbranch_execnz .LBB0_398

; __device__ __forceinline__ float bflo(unsigned w) { return __uint_as_float(w << 16); }
; __device__ __forceinline__ float bfhi(unsigned w) { return __uint_as_float(w & 0xffff0000u); }
; template <bool OUT_F32>
; __device__ __forceinline__ void norm_rows_from_bf16(const bf16_t* H, const float* gain, bf16_t* OB, float* OF, int gw, int NGW, int lane) {
;     for (int m = gw; m < NTOK; m += NGW) {
;         const u32x4* hr = (const u32x4*)(H + (size_t)m * DM) + lane;
;         u32x4 q[4]; float v[4][8]; float s = 0.f;
; #pragma unroll
;         for (int j = 0; j < 4; ++j) q[j] = __builtin_nontemporal_load(hr + 64 * j);
; #pragma unroll
;         for (int j = 0; j < 4; ++j) { v[j][0] = bflo(q[j].x); v[j][1] = bfhi(q[j].x); v[j][2] = bflo(q[j].y); v[j][3] = bfhi(q[j].y); v[j][4] = bflo(q[j].z); v[j][5] = bfhi(q[j].z); v[j][6] = bflo(q[j].w); v[j][7] = bfhi(q[j].w);
; #pragma unroll
;             for (int e = 0; e < 8; ++e) s += v[j][e] * v[j][e]; }
;         const float rstd = 1.0f / sqrtf(wave_sum(s) * (1.0f / DM) + 1e-6f);
.LBB0_953:
	s_cmpk_gt_i32 s54, 0x3fff
	v_mbcnt_lo_u32_b32 v12, -1, 0
	v_mbcnt_hi_u32_b32 v12, -1, v12
	s_cbranch_scc1 .LBB0_956
	v_mbcnt_lo_u32_b32 v0, -1, 0
	v_mbcnt_hi_u32_b32 v0, -1, v0
	s_waitcnt lgkmcnt(0)
	v_and_b32_e32 v1, 64, v0
	v_add_u32_e32 v1, 64, v1
	v_xor_b32_e32 v2, 1, v0
	v_cmp_lt_i32_e32 vcc, v2, v1
	s_ashr_i32 s55, s54, 31
	s_lshl_b64 s[0:1], s[54:55], 12
	v_cndmask_b32_e32 v2, v0, v2, vcc
	v_lshlrev_b32_e32 v16, 2, v2
	v_xor_b32_e32 v2, 2, v0
	v_cmp_lt_i32_e32 vcc, v2, v1
	v_lshlrev_b32_e32 v8, 3, v12
	s_add_u32 s0, s90, s0
	v_cndmask_b32_e32 v2, v0, v2, vcc
	v_lshlrev_b32_e32 v17, 2, v2
	v_xor_b32_e32 v2, 4, v0
	v_cmp_lt_i32_e32 vcc, v2, v1
	v_ashrrev_i32_e32 v13, 31, v12
	v_ashrrev_i32_e32 v9, 31, v8
	v_cndmask_b32_e32 v2, v0, v2, vcc
	v_lshlrev_b32_e32 v18, 2, v2
	v_xor_b32_e32 v2, 8, v0
	v_cmp_lt_i32_e32 vcc, v2, v1
	s_addc_u32 s1, s91, s1
	v_add_u32_e32 v4, 0x400, v8
	v_cndmask_b32_e32 v2, v0, v2, vcc
	v_lshlrev_b32_e32 v19, 2, v2
	v_xor_b32_e32 v2, 16, v0
	v_cmp_lt_i32_e32 vcc, v2, v1
	v_lshl_add_u64 v[12:13], v[12:13], 4, s[0:1]
	s_mov_b64 s[0:1], 0x1a800000
	v_cndmask_b32_e32 v2, v0, v2, vcc
	v_lshlrev_b32_e32 v20, 2, v2
	v_xor_b32_e32 v2, 32, v0
	v_cmp_lt_i32_e32 vcc, v2, v1
	s_ashr_i32 s93, s92, 31
	v_ashrrev_i32_e32 v5, 31, v4
	v_cndmask_b32_e32 v0, v0, v2, vcc
	v_lshlrev_b32_e32 v21, 2, v0
	v_lshlrev_b64 v[0:1], 2, v[8:9]
	v_add_u32_e32 v8, 0x600, v8
	v_ashrrev_i32_e32 v9, 31, v8
	v_lshl_add_u64 v[12:13], v[12:13], 0, s[0:1]
	s_lshl_b64 s[2:3], s[92:93], 12
	s_lshl_b64 s[0:1], s[54:55], 13
	v_lshlrev_b64 v[4:5], 2, v[4:5]
	v_lshlrev_b64 v[8:9], 2, v[8:9]
	s_add_u32 s4, s88, s0
	v_lshl_add_u64 v[2:3], s[64:65], 0, v[0:1]
	v_lshl_add_u64 v[6:7], s[64:65], 0, v[4:5]
	v_lshl_add_u64 v[10:11], s[64:65], 0, v[8:9]
	s_addc_u32 s5, s89, s1
	s_lshl_b64 s[6:7], s[92:93], 13
	v_mov_b32_e32 v22, 0x358637bd
	s_mov_b32 s8, 0xf800000
	v_mov_b32_e32 v23, 0x260
	global_load_dwordx4 v[96:99], v[2:3], off
	global_load_dwordx4 v[100:103], v[2:3], off offset:16
	global_load_dwordx4 v[104:107], v[2:3], off offset:2048
	global_load_dwordx4 v[108:111], v[2:3], off offset:2064
	global_load_dwordx4 v[112:115], v[6:7], off
	global_load_dwordx4 v[116:119], v[6:7], off offset:16
	global_load_dwordx4 v[120:123], v[10:11], off
	global_load_dwordx4 v[124:127], v[10:11], off offset:16
	global_load_dwordx4 v[128:131], v[12:13], off offset:3072 nt
	global_load_dwordx4 v[132:135], v[12:13], off nt
	global_load_dwordx4 v[136:139], v[12:13], off offset:1024 nt
	global_load_dwordx4 v[140:143], v[12:13], off offset:2048 nt
	s_waitcnt vmcnt(0)
	s_branch .Lfn_enter
.LBB0_955:
	s_waitcnt vmcnt(8)
.Lfn_enter:
	v_mov_b64_e32 v[24:25], v[128:129]
	v_mov_b64_e32 v[26:27], v[130:131]
	v_mov_b64_e32 v[28:29], v[132:133]
	v_mov_b64_e32 v[30:31], v[134:135]
	v_mov_b64_e32 v[32:33], v[136:137]
	v_mov_b64_e32 v[34:35], v[138:139]
	v_mov_b64_e32 v[36:37], v[140:141]
	v_mov_b64_e32 v[38:39], v[142:143]
	v_lshl_add_u64 v[48:49], s[4:5], 0, v[0:1]
	s_add_i32 s54, s54, s92
	s_cmpk_lt_i32 s54, 0x4000
	s_cselect_b32 s10, s2, 0
	s_cselect_b32 s11, s3, 0
	v_lshl_add_u64 v[12:13], v[12:13], 0, s[10:11]
	global_load_dwordx4 v[128:131], v[12:13], off offset:3072 nt
	global_load_dwordx4 v[132:135], v[12:13], off nt
	global_load_dwordx4 v[136:139], v[12:13], off offset:1024 nt
	global_load_dwordx4 v[140:143], v[12:13], off offset:2048 nt
	v_and_b32_e32 v14, 0xffff0000, v27
	v_lshlrev_b32_e32 v50, 16, v28
	v_and_b32_e32 v51, 0xffff0000, v28
	v_lshlrev_b32_e32 v15, 16, v27
	v_lshlrev_b32_e32 v28, 16, v29
	v_and_b32_e32 v29, 0xffff0000, v29
	v_lshlrev_b32_e32 v66, 16, v26
	v_and_b32_e32 v67, 0xffff0000, v26
	v_pk_mul_f32 v[26:27], v[50:51], v[50:51]
	v_pk_mul_f32 v[68:69], v[28:29], v[28:29]
	v_add_f32_e32 v26, v26, v27
	v_lshlrev_b32_e32 v52, 16, v30
	v_and_b32_e32 v53, 0xffff0000, v30
	v_add_f32_e32 v26, v68, v26
	v_pk_mul_f32 v[70:71], v[52:53], v[52:53]
	v_add_f32_e32 v26, v69, v26
	v_lshlrev_b32_e32 v30, 16, v31
	v_and_b32_e32 v31, 0xffff0000, v31
	v_add_f32_e32 v26, v70, v26
	v_pk_mul_f32 v[72:73], v[30:31], v[30:31]
	v_add_f32_e32 v26, v71, v26
	v_lshlrev_b32_e32 v54, 16, v32
	v_and_b32_e32 v55, 0xffff0000, v32
	v_add_f32_e32 v26, v72, v26
	v_pk_mul_f32 v[74:75], v[54:55], v[54:55]
	v_add_f32_e32 v26, v73, v26
	v_lshlrev_b32_e32 v32, 16, v33
	v_and_b32_e32 v33, 0xffff0000, v33
	v_add_f32_e32 v26, v74, v26
	v_pk_mul_f32 v[76:77], v[32:33], v[32:33]
	v_add_f32_e32 v26, v75, v26
	v_lshlrev_b32_e32 v56, 16, v34
	v_and_b32_e32 v57, 0xffff0000, v34
	v_add_f32_e32 v26, v76, v26
	v_pk_mul_f32 v[78:79], v[56:57], v[56:57]
	v_add_f32_e32 v26, v77, v26
	v_lshlrev_b32_e32 v34, 16, v35
	v_and_b32_e32 v35, 0xffff0000, v35
	v_add_f32_e32 v26, v78, v26
	v_pk_mul_f32 v[80:81], v[34:35], v[34:35]
	v_add_f32_e32 v26, v79, v26
	v_lshlrev_b32_e32 v58, 16, v36
	v_and_b32_e32 v59, 0xffff0000, v36
	v_add_f32_e32 v26, v80, v26
	v_pk_mul_f32 v[82:83], v[58:59], v[58:59]
	v_add_f32_e32 v26, v81, v26
	v_lshlrev_b32_e32 v36, 16, v37
	v_and_b32_e32 v37, 0xffff0000, v37
	v_add_f32_e32 v26, v82, v26
	v_pk_mul_f32 v[84:85], v[36:37], v[36:37]
	v_add_f32_e32 v26, v83, v26
	v_lshlrev_b32_e32 v60, 16, v38
	v_and_b32_e32 v61, 0xffff0000, v38
	v_add_f32_e32 v26, v84, v26
	v_pk_mul_f32 v[86:87], v[60:61], v[60:61]
	v_add_f32_e32 v26, v85, v26
	v_lshlrev_b32_e32 v38, 16, v39
	v_and_b32_e32 v39, 0xffff0000, v39
	v_add_f32_e32 v26, v86, v26
	v_pk_mul_f32 v[88:89], v[38:39], v[38:39]
	v_add_f32_e32 v26, v87, v26
	v_lshlrev_b32_e32 v62, 16, v24
	v_and_b32_e32 v63, 0xffff0000, v24
	v_add_f32_e32 v26, v88, v26
	v_pk_mul_f32 v[90:91], v[62:63], v[62:63]
	v_add_f32_e32 v26, v89, v26
	v_lshlrev_b32_e32 v64, 16, v25
	v_and_b32_e32 v65, 0xffff0000, v25
	v_add_f32_e32 v26, v90, v26
	v_pk_mul_f32 v[92:93], v[64:65], v[64:65]
	v_add_f32_e32 v26, v91, v26
	v_add_f32_e32 v26, v92, v26
	v_pk_mul_f32 v[94:95], v[66:67], v[66:67]
	v_add_f32_e32 v26, v93, v26
	v_add_f32_e32 v26, v94, v26
	v_pk_mul_f32 v[24:25], v[14:15], v[14:15]
	v_add_f32_e32 v26, v95, v26
	v_add_f32_e32 v25, v25, v26
	v_add_f32_e32 v24, v24, v25
	ds_bpermute_b32 v25, v16, v24
	s_waitcnt lgkmcnt(0)
; template <bool OUT_F32>
; __device__ __forceinline__ void norm_rows_from_bf16(const bf16_t* H, const float* gain, bf16_t* OB, float* OF, int gw, int NGW, int lane) {
;     ...
;         const float rstd = 1.0f / sqrtf(wave_sum(s) * (1.0f / DM) + 1e-6f);
; #pragma unroll
;         for (int j = 0; j < 4; ++j) {
;             const int c0 = 8 * (lane + 64 * j);
;             const f32x4 g0 = *(const f32x4*)(gain + c0), g1 = *(const f32x4*)(gain + c0 + 4);
;             const float o0 = v[j][0] * rstd * g0[0], o1 = v[j][1] * rstd * g0[1], o2 = v[j][2] * rstd * g0[2], o3 = v[j][3] * rstd * g0[3];
;             const float o4 = v[j][4] * rstd * g1[0], o5 = v[j][5] * rstd * g1[1], o6 = v[j][6] * rstd * g1[2], o7 = v[j][7] * rstd * g1[3];
;             if (OUT_F32) { float* op = OF + (size_t)m * DM + c0; __builtin_nontemporal_store((f32x4){o0, o1, o2, o3}, (f32x4*)op); __builtin_nontemporal_store((f32x4){o4, o5, o6, o7}, (f32x4*)(op + 4)); }
;             else { u32x4 w; w.x = pk2(o0, o1); w.y = pk2(o2, o3); w.z = pk2(o4, o5); w.w = pk2(o6, o7); *(u32x4*)(OB + (size_t)m * DM + c0) = w; }
	v_add_f32_e32 v24, v24, v25
	ds_bpermute_b32 v25, v17, v24
	s_waitcnt lgkmcnt(0)
	v_add_f32_e32 v24, v24, v25
	ds_bpermute_b32 v25, v18, v24
	s_waitcnt lgkmcnt(0)
	v_add_f32_e32 v24, v24, v25
	ds_bpermute_b32 v25, v19, v24
	s_waitcnt lgkmcnt(0)
	v_add_f32_e32 v24, v24, v25
	ds_bpermute_b32 v25, v20, v24
	s_waitcnt lgkmcnt(0)
	v_add_f32_e32 v24, v24, v25
	ds_bpermute_b32 v25, v21, v24
	s_waitcnt lgkmcnt(0)
	v_add_f32_e32 v24, v24, v25
	v_fmamk_f32 v24, v24, 0x3a000000, v22
	v_mul_f32_e32 v25, 0x4f800000, v24
	v_cmp_gt_f32_e32 vcc, s8, v24
	s_nop 1
	v_cndmask_b32_e32 v24, v24, v25, vcc
	v_sqrt_f32_e32 v25, v24
	s_nop 0
	v_add_u32_e32 v26, -1, v25
	v_add_u32_e32 v27, 1, v25
	v_fma_f32 v68, -v26, v25, v24
	v_fma_f32 v69, -v27, v25, v24
	v_cmp_ge_f32_e64 s[0:1], 0, v68
	s_nop 1
	v_cndmask_b32_e64 v25, v25, v26, s[0:1]
	v_cmp_lt_f32_e64 s[0:1], 0, v69
	s_nop 1
	v_cndmask_b32_e64 v25, v25, v27, s[0:1]
	v_mul_f32_e32 v26, 0x37800000, v25
	v_cndmask_b32_e32 v25, v25, v26, vcc
	v_cmp_class_f32_e32 vcc, v24, v23
	s_nop 1
	v_cndmask_b32_e32 v24, v25, v24, vcc
	v_div_scale_f32 v25, s[0:1], v24, v24, 1.0
	v_rcp_f32_e32 v27, v25
	v_div_scale_f32 v26, vcc, 1.0, v24, 1.0
	v_fma_f32 v68, -v25, v27, 1.0
	v_fmac_f32_e32 v27, v68, v27
	v_mul_f32_e32 v68, v26, v27
	v_fma_f32 v69, -v25, v68, v26
	v_fmac_f32_e32 v68, v69, v27
	v_fma_f32 v25, -v25, v68, v26
	v_div_fmas_f32 v25, v25, v27, v68
	v_div_fixup_f32 v68, v25, v24, 1.0
	v_pk_mul_f32 v[24:25], v[68:69], v[50:51] op_sel_hi:[0,1]
	v_pk_mul_f32 v[26:27], v[68:69], v[28:29] op_sel_hi:[0,1]
	v_pk_mul_f32 v[28:29], v[68:69], v[52:53] op_sel_hi:[0,1]
	v_pk_mul_f32 v[30:31], v[68:69], v[30:31] op_sel_hi:[0,1]
	v_pk_mul_f32 v[26:27], v[98:99], v[26:27]
	v_pk_mul_f32 v[24:25], v[96:97], v[24:25]
	v_pk_mul_f32 v[30:31], v[102:103], v[30:31]
	v_pk_mul_f32 v[28:29], v[100:101], v[28:29]
	global_store_dwordx4 v[48:49], v[24:27], off nt
	global_store_dwordx4 v[48:49], v[28:31], off offset:16 nt
	v_pk_mul_f32 v[32:33], v[68:69], v[32:33] op_sel_hi:[0,1]
	v_pk_mul_f32 v[40:41], v[68:69], v[54:55] op_sel_hi:[0,1]
	v_pk_mul_f32 v[34:35], v[68:69], v[34:35] op_sel_hi:[0,1]
	v_pk_mul_f32 v[42:43], v[68:69], v[56:57] op_sel_hi:[0,1]
	v_pk_mul_f32 v[38:39], v[68:69], v[38:39] op_sel_hi:[0,1]
	v_pk_mul_f32 v[14:15], v[68:69], v[14:15] op_sel_hi:[0,1]
	v_pk_mul_f32 v[24:25], v[104:105], v[40:41]
	v_pk_mul_f32 v[26:27], v[106:107], v[32:33]
	v_pk_mul_f32 v[28:29], v[108:109], v[42:43]
	v_pk_mul_f32 v[30:31], v[110:111], v[34:35]
	global_store_dwordx4 v[48:49], v[24:27], off offset:2048 nt
	global_store_dwordx4 v[48:49], v[28:31], off offset:2064 nt
	v_pk_mul_f32 v[34:35], v[68:69], v[36:37] op_sel_hi:[0,1]
	v_pk_mul_f32 v[36:37], v[68:69], v[58:59] op_sel_hi:[0,1]
	v_lshl_add_u64 v[32:33], s[4:5], 0, v[4:5]
	v_pk_mul_f32 v[40:41], v[68:69], v[60:61] op_sel_hi:[0,1]
	v_pk_mul_f32 v[24:25], v[112:113], v[36:37]
	v_pk_mul_f32 v[26:27], v[114:115], v[34:35]
	v_pk_mul_f32 v[28:29], v[116:117], v[40:41]
	v_pk_mul_f32 v[30:31], v[118:119], v[38:39]
	global_store_dwordx4 v[32:33], v[24:27], off nt
	global_store_dwordx4 v[32:33], v[28:31], off offset:16 nt
	v_lshl_add_u64 v[32:33], s[4:5], 0, v[8:9]
	s_add_u32 s4, s4, s6
	s_addc_u32 s5, s5, s7
	v_pk_mul_f32 v[36:37], v[68:69], v[64:65] op_sel_hi:[0,1]
	v_pk_mul_f32 v[38:39], v[68:69], v[62:63] op_sel_hi:[0,1]
	s_cmpk_lt_i32 s54, 0x4000
	v_pk_mul_f32 v[34:35], v[68:69], v[66:67] op_sel_hi:[0,1]
	v_pk_mul_f32 v[24:25], v[120:121], v[38:39]
	v_pk_mul_f32 v[26:27], v[122:123], v[36:37]
	v_pk_mul_f32 v[28:29], v[124:125], v[34:35]
	v_pk_mul_f32 v[30:31], v[126:127], v[14:15] op_sel:[0,1] op_sel_hi:[1,0]
	global_store_dwordx4 v[32:33], v[24:27], off nt
	global_store_dwordx4 v[32:33], v[28:31], off offset:16 nt
	s_cbranch_scc1 .LBB0_955
